# indexer selection: histogram suffix scan via row DPP + readlane (exact integer adds), crossing-bin broadcast via v_readlane instead of ds_bpermute
# speedup vs baseline: 1.0085x; 1.0085x over previous
; #define LAS __attribute__((address_space(3)))
; __device__ __forceinline__ void indexer_phase(const bf16_t* PJ, float* rk, unsigned short* SEL, LAS unsigned char* lds) {
;     ...
;                 unsigned c[8]; unsigned lsum = 0;
;                 { const u32x4 h0 = *(const LAS u32x4*)(hist + 8 * lane), h1 = *(const LAS u32x4*)(hist + 8 * lane + 4);
;                   c[0] = h0.x; c[1] = h0.y; c[2] = h0.z; c[3] = h0.w; c[4] = h1.x; c[5] = h1.y; c[6] = h1.z; c[7] = h1.w; }
; #pragma unroll
;                 for (int i = 0; i < 8; ++i) lsum += c[i];
;                 unsigned sfx = lsum;
; #pragma unroll
;                 for (int o = 1; o < 64; o <<= 1) { const unsigned x = __shfl_down(sfx, o); if (lane + o < 64) sfx += x; }
;                 unsigned cum = sfx - lsum; int bst = -1; unsigned cab = 0, ceq = 0;
; #pragma unroll
;                 for (int i = 7; i >= 0; --i) { if (cum < need && cum + c[i] >= need) { bst = 8 * lane + i; cab = cum; ceq = c[i]; } cum += c[i]; }
;                 const unsigned long long bm = __ballot(bst >= 0);
;                 const int src = __builtin_amdgcn_readfirstlane((int)__builtin_ctzll(bm));
;                 const int bstar = __builtin_amdgcn_readfirstlane(__shfl(bst, src));
;                 const unsigned cnt_above = (unsigned)__builtin_amdgcn_readfirstlane((int)__shfl(cab, src)), cnt_eq = (unsigned)__builtin_amdgcn_readfirstlane((int)__shfl(ceq, src));
;                 need -= cnt_above;
.LBB0_906:
	s_waitcnt lgkmcnt(0)
	s_waitcnt lgkmcnt(5)
	ds_read_b128 v[0:3], v119
	ds_read_b128 v[66:69], v119 offset:16
	s_waitcnt lgkmcnt(0)
	s_waitcnt lgkmcnt(1)
	v_add_u32_e32 v7, v1, v0
	v_add3_u32 v7, v7, v2, v3
	s_waitcnt lgkmcnt(0)
	v_add3_u32 v7, v7, v66, v67
	v_add3_u32 v7, v7, v68, v69
	v_mov_b32_e32 v9, v7
	s_nop 1
	v_add_u32_dpp v9, v9, v9 row_shl:1 row_mask:0xf bank_mask:0xf
	s_nop 1
	v_add_u32_dpp v9, v9, v9 row_shl:2 row_mask:0xf bank_mask:0xf
	s_nop 1
	v_add_u32_dpp v9, v9, v9 row_shl:4 row_mask:0xf bank_mask:0xf
	s_nop 1
	v_add_u32_dpp v9, v9, v9 row_shl:8 row_mask:0xf bank_mask:0xf
	s_nop 1
	v_cmp_gt_u32_e32 vcc, 16, v108
	v_readlane_b32 s28, v9, 48
	v_readlane_b32 s29, v9, 32
	v_readlane_b32 s3, v9, 16
	s_add_u32 s29, s29, s28
	s_add_u32 s3, s3, s29
	v_mov_b32_e32 v13, s28
	v_mov_b32_e32 v15, s29
	v_mov_b32_e32 v17, s3
	v_cndmask_b32_e64 v13, 0, v13, s[20:21]
	v_cndmask_b32_e64 v13, v13, v15, s[22:23]
	v_cndmask_b32_e32 v13, v13, v17, vcc
	v_add_u32_e32 v9, v9, v13
	v_sub_u32_e32 v7, v9, v7
	v_add_u32_e32 v9, v7, v69
	v_cmp_le_u32_e32 vcc, s55, v7
	v_cmp_gt_u32_e64 s[28:29], s55, v9
	s_or_b64 s[28:29], vcc, s[28:29]
	v_add_u32_e32 v17, v9, v68
	v_cndmask_b32_e64 v13, v69, 0, s[28:29]
	v_cndmask_b32_e64 v7, v7, 0, s[28:29]
	v_cndmask_b32_e64 v15, v161, -1, s[28:29]
	v_cmp_le_u32_e32 vcc, s55, v9
	v_cmp_gt_u32_e64 s[28:29], s55, v17
	s_or_b64 vcc, vcc, s[28:29]
	v_cndmask_b32_e32 v7, v9, v7, vcc
	v_cndmask_b32_e32 v9, v162, v15, vcc
	v_add_u32_e32 v15, v17, v67
	v_cndmask_b32_e32 v13, v68, v13, vcc
	v_cmp_le_u32_e32 vcc, s55, v17
	v_cmp_gt_u32_e64 s[28:29], s55, v15
	s_or_b64 vcc, vcc, s[28:29]
	v_cndmask_b32_e32 v7, v17, v7, vcc
	v_add_u32_e32 v17, v15, v66
	v_cndmask_b32_e32 v13, v67, v13, vcc
	v_cndmask_b32_e32 v9, v163, v9, vcc
	v_cmp_le_u32_e32 vcc, s55, v15
	v_cmp_gt_u32_e64 s[28:29], s55, v17
	s_or_b64 vcc, vcc, s[28:29]
	v_cndmask_b32_e32 v7, v15, v7, vcc
	v_add_u32_e32 v15, v17, v3
	v_cndmask_b32_e32 v13, v66, v13, vcc
	v_cndmask_b32_e32 v9, v164, v9, vcc
	v_cmp_le_u32_e32 vcc, s55, v17
	v_cmp_gt_u32_e64 s[28:29], s55, v15
	s_or_b64 vcc, vcc, s[28:29]
	v_cndmask_b32_e32 v3, v3, v13, vcc
	v_add_u32_e32 v13, v15, v2
	v_cndmask_b32_e32 v7, v17, v7, vcc
	v_cndmask_b32_e32 v9, v165, v9, vcc
	v_cmp_le_u32_e32 vcc, s55, v15
	v_cmp_gt_u32_e64 s[28:29], s55, v13
	s_or_b64 vcc, vcc, s[28:29]
	v_cndmask_b32_e32 v2, v2, v3, vcc
	v_cndmask_b32_e32 v3, v15, v7, vcc
	v_cndmask_b32_e32 v7, v166, v9, vcc
	v_add_u32_e32 v9, v13, v1
	v_cmp_le_u32_e32 vcc, s55, v13
	v_cmp_gt_u32_e64 s[28:29], s55, v9
	s_or_b64 vcc, vcc, s[28:29]
	v_cndmask_b32_e32 v1, v1, v2, vcc
	v_cndmask_b32_e32 v2, v13, v3, vcc
	v_cndmask_b32_e32 v3, v167, v7, vcc
	v_add_u32_e32 v7, v9, v0
	v_cmp_le_u32_e32 vcc, s55, v9
	v_cmp_gt_u32_e64 s[28:29], s55, v7
	s_or_b64 vcc, vcc, s[28:29]
	v_cndmask_b32_e32 v0, v0, v1, vcc
	v_cndmask_b32_e32 v1, v9, v2, vcc
	v_cndmask_b32_e32 v2, v117, v3, vcc
	v_cmp_lt_i32_e32 vcc, -1, v2
	s_ff1_i32_b64 s1, vcc
	v_readlane_b32 s95, v0, s1
	v_readlane_b32 s59, v2, s1
	v_readlane_b32 s3, v1, s1
	s_mov_b64 s[28:29], -1
	s_cmp_gt_u32 s95, 64
	v_mov_b32_e32 v0, s95
	v_mov_b32_e32 v2, s59
	v_mov_b32_e32 v1, s3
	s_cselect_b64 s[90:91], -1, 0
	s_andn2_b64 vcc, exec, s[30:31]
	s_cbranch_vccnz .LBB0_924
	s_and_b64 vcc, exec, s[26:27]
	s_cbranch_vccnz .LBB0_959
	s_cmp_eq_u32 s57, 1
	s_mov_b32 s75, 0
	v_mov_b32_e32 v7, 0xff800000
	v_mov_b32_e32 v9, 0x7f800000
	s_cselect_b64 s[92:93], -1, 0
	v_mov_b32_e32 v0, v111
	v_mov_b32_e32 v1, v118
	s_mov_b32 s1, s74
	v_mov_b32_e32 v2, v5
	s_branch .LBB0_911
